# phase-3 GEMM tiles assigned with the XCD-aware block permutation phase 1 already uses
# baseline (speedup 1.0000x reference)
; #define LAUNDER_TID(t) int t = (g_wave << 6) | (int)__builtin_amdgcn_mbcnt_hi(~0u, __builtin_amdgcn_mbcnt_lo(~0u, 0u)); asm volatile("" : "+v"(t))
; #define G_STAGE_B(bufoff, upn, kt_, h_) do { const char* _g = Bbase + ((size_t)((upn) * 256 + (h_) * 128) * K + (size_t)(kt_) * 64) * 2; \
;     _Pragma("unroll") for (int _i = 0; _i < 2; ++_i) \
;       __builtin_amdgcn_global_load_lds((const unsigned*)(_g + voffB[_i]), (LAS unsigned*)(lds + (bufoff) + ldsw + _i * 8192), 16, 0, 0); } while (0)
; #define G_WAIT_V(n) asm volatile("s_waitcnt vmcnt(" #n ")" ::: "memory")
; #define G_BAR __builtin_amdgcn_s_barrier()
; template <int MODE> DI bool gemm_unit(int i, int& pm, int& pn) {
;     ...
;     const int v = i * 256 + blockIdx.x;
;     if (v >= 258 * 4) return false;
;     pm = v >> 2; pn = v & 3; return true;
; template <int MODE>
; DI void gemm_phase(const Params& p, char* smem, const int g_wave) {
;     ...
;   LAUNDER_TID(tid);
;   const int wid = __builtin_amdgcn_readfirstlane(tid >> 6), lane = tid & 63, wr = wid >> 2, wc = wid & 3, fr = lane & 15, fq = lane >> 4;
;   unsigned voffA0[2], voffA1[2], voffB[2];
; #pragma unroll
;   for (int i = 0; i < 2; ++i) { int R, C; stage_rc(tid * 16 + i * 8192, R, C);
;     const int Rb = (R & ~31) + perm32(R & 31);
;     voffA0[i] = (unsigned)(R * 1024 + C) * 2u; voffA1[i] = (unsigned)(R * 3200 + C) * 2u; voffB[i] = (unsigned)(Rb * K + C) * 2u; }
;   const unsigned ldsw = (unsigned)wid * 1024u;
;   const int aoff = lds_byte(wr * 64 + fr, fq * 8), boff = lds_byte(wc * 32 + fr, fq * 8);
;   const char* Bbase = p.ws + (MODE == 0 ? WS_WINT : WS_WOUTT);
;     ...
;   int cpm, cpn, npm = 0, npn = 0, ui = 0;
;   if (!gemm_unit<MODE>(0, cpm, cpn)) return;
;   f32x4 acc[2][2][4][2];
; #pragma unroll
;   for (int a = 0; a < 2; ++a)
; #pragma unroll
;     for (int b = 0; b < 2; ++b)
; #pragma unroll
;       for (int m = 0; m < 4; ++m)
; #pragma unroll
;         for (int n = 0; n < 2; ++n) acc[a][b][m][n] = (f32x4){0.f, 0.f, 0.f, 0.f};
;   bf16x8 At[4][2], B0[2][2], B1[2][2];
;   G_STAGE_B(G_SB(0, 0), cpn, 0, 0); G_STAGE_A(G_SA(0, 0), cpm, 0, 0); G_STAGE_B(G_SB(0, 1), cpn, 0, 1); G_STAGE_A(G_SA(0, 1), cpm, 0, 1);
;   if (wr == 1) G_BAR;
;   G_WAIT_V(4); G_BAR;
.LBB0_812:
	s_cmp_lt_i32 s74, 4
	s_cselect_b64 s[0:1], -1, 0
	s_cmp_gt_i32 s84, 3
	s_cselect_b64 s[2:3], -1, 0
	s_and_b64 s[0:1], s[0:1], s[2:3]
	s_andn2_b64 vcc, exec, s[0:1]
	s_cbranch_vccnz .LBB0_851
	s_and_b32 s0, s75, 0xffffffc0
	v_mbcnt_hi_u32_b32 v2, -1, v1
	v_or_b32_e32 v8, s0, v2
	v_readlane_b32 s0, v255, 0
	s_nop 3
	s_and_b32 s1, s0, 7
	s_lshl_b32 s1, s1, 5
	s_lshr_b32 s0, s0, 3
	s_or_b32 s0, s0, s1
	s_nop 0
	v_writelane_b32 v255, s0, 51
	s_nop 1
	v_readlane_b32 s0, v255, 51
	s_cmpk_gt_i32 s0, 0x407
	v_readfirstlane_b32 s2, v8
	v_readlane_b32 s1, v255, 1
	s_cbranch_scc1 .LBB0_839
	v_ashrrev_i32_e32 v3, 31, v8
	v_lshrrev_b32_e32 v3, 26, v3
	v_add_u32_e32 v3, v8, v3
	v_ashrrev_i32_e32 v6, 6, v3
	v_bfe_i32 v3, v8, 27, 1
	v_lshlrev_b32_e32 v2, 4, v8
	v_lshrrev_b32_e32 v3, 22, v3
	v_add_u32_e32 v3, v2, v3
	v_and_b32_e32 v3, 0xfffffc00, v3
	v_sub_u32_e32 v3, v2, v3
	v_lshrrev_b32_e32 v4, 4, v3
	v_bitop3_b32 v3, v4, v3, 32 bitop3:0x6c
	v_ashrrev_i32_e32 v5, 31, v3
	v_lshrrev_b32_e32 v5, 26, v5
	v_add_u32_e32 v5, v3, v5
	v_ashrrev_i32_e32 v7, 6, v5
	v_and_b32_e32 v5, 0xc0, v5
	v_sub_u32_e32 v3, v3, v5
	v_mov_b32_e32 v5, 1
	v_ashrrev_i16_sdwa v3, v5, sext(v3) dst_sel:DWORD dst_unused:UNUSED_PAD src0_sel:DWORD src1_sel:BYTE_0
	v_add_u32_e32 v2, 0x2000, v2
	v_bfe_i32 v10, v3, 0, 16
	v_ashrrev_i32_e32 v3, 31, v2
	v_lshrrev_b32_e32 v3, 22, v3
	v_add_u32_e32 v3, v2, v3
	v_ashrrev_i32_e32 v9, 10, v3
	v_lshlrev_b32_e32 v4, 3, v6
	v_mul_i32_i24_e32 v3, 0x400, v9
	v_and_b32_e32 v4, -16, v4
	v_sub_u32_e32 v2, v2, v3
	v_add_u32_e32 v13, v7, v4
	v_lshlrev_b32_e32 v4, 5, v6
	v_lshrrev_b32_e32 v3, 4, v2
	v_and_b32_e32 v4, 32, v4
	v_bitop3_b32 v2, v3, v2, 32 bitop3:0x6c
	v_add_u32_e32 v14, v4, v10
	v_ashrrev_i32_e32 v4, 31, v2
	v_lshrrev_b32_e32 v4, 26, v4
	v_add_u32_e32 v4, v2, v4
	v_lshlrev_b32_e32 v3, 3, v9
	v_ashrrev_i32_e32 v11, 6, v4
	v_and_b32_e32 v4, 0xc0, v4
	v_and_b32_e32 v3, -16, v3
	v_sub_u32_e32 v2, v2, v4
	s_ashr_i32 s8, s2, 6
	s_ashr_i32 s6, s2, 8
	v_add_u32_e32 v15, v11, v3
	v_lshlrev_b32_e32 v3, 5, v9
	v_ashrrev_i16_sdwa v2, v5, sext(v2) dst_sel:DWORD dst_unused:UNUSED_PAD src0_sel:DWORD src1_sel:BYTE_0
	s_lshl_b32 s4, s8, 10
	v_and_b32_e32 v3, 32, v3
	v_bfe_i32 v12, v2, 0, 16
	s_add_u32 s3, s72, 0x1101000
	v_readlane_b32 s0, v255, 51
	v_add_u32_e32 v16, v3, v12
	s_addc_u32 s26, s73, 0
	s_and_b32 s7, s0, 3
	s_ashr_i32 s38, s0, 2
	v_and_b32_e32 v2, 3, v11
	s_mov_b32 s0, 0xfffe0
	v_lshrrev_b32_e32 v3, 2, v15
	v_lshlrev_b32_e32 v4, 1, v15
	v_and_or_b32 v2, v15, s0, v2
	v_and_b32_e32 v3, 4, v3
	v_and_b32_e32 v4, 24, v4
	v_or3_b32 v2, v2, v3, v4
	v_lshlrev_b32_e32 v3, 1, v16
	v_lshl_add_u32 v194, v2, 12, v3
	v_and_b32_e32 v2, 3, v7
	v_and_or_b32 v2, v13, s0, v2
	s_lshl_b32 s0, s7, 20
	v_readlane_b32 s1, v255, 1
	s_add_u32 s0, s3, s0
	s_addc_u32 s1, s26, 0
	s_add_i32 s27, s4, 16
	s_add_i32 s28, s27, 0x10000
	s_add_i32 s29, s27, 0x12000
	v_lshl_add_u32 v196, v15, 11, v3
	v_lshrrev_b32_e32 v3, 2, v13
	v_lshlrev_b32_e32 v4, 1, v13
	s_add_u32 s30, s72, 0x9641000
	v_and_b32_e32 v3, 4, v3
	v_and_b32_e32 v4, 24, v4
	s_addc_u32 s31, s73, 0
	s_lshl_b32 s10, s38, 8
	v_or3_b32 v2, v2, v3, v4
	v_lshlrev_b32_e32 v3, 1, v14
	s_ashr_i32 s11, s10, 31
	v_lshl_add_u32 v198, v2, 12, v3
	s_mov_b32 m0, s28
	s_lshl_b64 s[4:5], s[10:11], 11
	global_load_lds_dwordx4 v198, s[0:1]
	s_mov_b32 m0, s29
	s_add_u32 s16, s30, s4
	s_waitcnt lgkmcnt(0)
	v_lshl_add_u32 v200, v13, 11, v3
	global_load_lds_dwordx4 v194, s[0:1]
	s_addc_u32 s17, s31, s5
	s_mov_b32 m0, s27
	s_add_i32 s33, s27, 0x2000
	global_load_lds_dwordx4 v200, s[16:17]
	s_mov_b32 m0, s33
	v_mov_b32_e32 v199, 0
	global_load_lds_dwordx4 v196, s[16:17]
	s_add_u32 s16, s0, 0x80000
	s_addc_u32 s17, s1, 0
	s_bitset1_b32 s10, 7
	s_ashr_i32 s11, s10, 31
	s_add_i32 s34, s27, 0x14000
	s_add_i32 s35, s27, 0x16000
	s_lshl_b64 s[10:11], s[10:11], 11
	s_mov_b32 m0, s34
	s_add_u32 s10, s30, s10
	global_load_lds_dwordx4 v198, s[16:17]
	s_mov_b32 m0, s35
	s_addc_u32 s11, s31, s11
	s_add_i32 s36, s27, 0x4000
	global_load_lds_dwordx4 v194, s[16:17]
	s_mov_b32 m0, s36
	s_add_i32 s37, s27, 0x6000
	global_load_lds_dwordx4 v200, s[10:11]
	s_mov_b32 m0, s37
	v_mov_b32_e32 v195, v199
	global_load_lds_dwordx4 v196, s[10:11]
	v_lshl_add_u64 v[4:5], s[0:1], 0, v[198:199]
	v_lshl_add_u64 v[2:3], s[0:1], 0, v[194:195]
	v_mov_b32_e32 v201, v199
	s_cmp_lg_u32 s6, 1
	v_mov_b32_e32 v197, v199
	s_cbranch_scc1 .LBB0_816
	s_barrier
; #define G_STAGE_B(bufoff, upn, kt_, h_) do { const char* _g = Bbase + ((size_t)((upn) * 256 + (h_) * 128) * K + (size_t)(kt_) * 64) * 2; \
;     _Pragma("unroll") for (int _i = 0; _i < 2; ++_i) \
;       __builtin_amdgcn_global_load_lds((const unsigned*)(_g + voffB[_i]), (LAS unsigned*)(lds + (bufoff) + ldsw + _i * 8192), 16, 0, 0); } while (0)
; #define G_WAIT_V(n) asm volatile("s_waitcnt vmcnt(" #n ")" ::: "memory")
; #define G_BAR __builtin_amdgcn_s_barrier()
; template <int MODE> DI bool gemm_unit(int i, int& pm, int& pn) {
;     ...
;     const int v = i * 256 + blockIdx.x;
;     if (v >= 258 * 4) return false;
;     pm = v >> 2; pn = v & 3; return true;
; template <int MODE>
; DI void gemm_phase(const Params& p, char* smem, const int g_wave) {
;     ...
;   G_STAGE_B(G_SB(1, 0), cpn, 1, 0); G_STAGE_A(G_SA(1, 0), cpm, 1, 0); G_STAGE_B(G_SB(1, 1), cpn, 1, 1);
;   G_WAIT_V(6); G_BAR;
;   for (;;) {
;     const bool has_next = gemm_unit<MODE>(ui + 1, npm, npn);
;     if (!has_next) { npm = cpm; npn = cpn; }
; #pragma unroll 1
;     for (int t = 0; t < nt; t += 2) {
;       const bool last = (t == nt - 2);
;       const int pm2 = last ? npm : cpm, pn2 = last ? npn : cpn, t2 = last ? 0 : t + 2, t3 = t2 + 1;
.LBB0_816:
	s_lshl_b32 s8, s8, 5
	s_and_b32 s11, s8, 0x60
	s_lshl_b32 s10, s6, 13
	s_lshl_b32 s16, s11, 7
	s_add_i32 s39, s27, 0x18000
	s_add_i32 s40, s27, 0x1a000
	s_add_u32 s4, s72, s4
	s_mov_b64 s[8:9], 0x80
	s_addc_u32 s5, s73, s5
	v_lshl_add_u64 v[4:5], v[4:5], 0, s[8:9]
	s_mov_b32 m0, s39
	s_add_u32 s4, s4, 0x9641080
	s_waitcnt vmcnt(4)
	s_barrier
	global_load_lds_dwordx4 v[4:5], off
	v_lshl_add_u64 v[2:3], v[2:3], 0, s[8:9]
	s_mov_b32 m0, s40
	s_addc_u32 s5, s5, 0
	s_add_i32 s41, s27, 0x8000
	s_add_i32 s42, s27, 0xa000
	global_load_lds_dwordx4 v[2:3], off
	v_lshl_add_u64 v[2:3], s[4:5], 0, v[200:201]
	s_mov_b32 m0, s41
	s_add_u32 s0, s0, 0x80080
	global_load_lds_dwordx4 v[2:3], off
	v_lshl_add_u64 v[2:3], s[4:5], 0, v[196:197]
	s_mov_b32 m0, s42
	s_addc_u32 s1, s1, 0
	s_add_i32 s43, s27, 0x1c000
	global_load_lds_dwordx4 v[2:3], off
	v_lshl_add_u64 v[2:3], s[0:1], 0, v[198:199]
	s_mov_b32 m0, s43
	s_add_i32 s44, s27, 0x1e000
	global_load_lds_dwordx4 v[2:3], off
	v_lshl_add_u64 v[2:3], s[0:1], 0, v[194:195]
	s_mov_b32 m0, s44
	s_lshl_b32 s45, s7, 19
	global_load_lds_dwordx4 v[2:3], off
	s_movk_i32 s0, 0xc80
	s_or_b32 s46, s45, 0x40000
	v_mul_lo_u32 v2, v13, s0
	v_lshrrev_b32_e32 v3, 1, v8
	s_add_u32 s47, s72, 0x23941000
	v_add_lshl_u32 v202, v14, v2, 1
	v_mul_lo_u32 v2, v15, s0
	v_and_b32_e32 v3, 24, v3
	s_addc_u32 s48, s73, 0
	s_lshl_b32 s0, s7, 10
	v_add_lshl_u32 v204, v16, v2, 1
	v_and_b32_e32 v2, 15, v8
	v_lshlrev_b32_e32 v4, 1, v3
	s_add_u32 s0, s70, s0
	v_lshl_or_b32 v219, s6, 6, v2
	v_lshl_or_b32 v2, v2, 6, v4
	v_lshlrev_b32_e32 v4, 2, v8
	s_addc_u32 s5, s71, 0
	s_lshl_b32 s4, s11, 2
	v_and_b32_e32 v4, 32, v4
	s_add_u32 s4, s0, s4
	v_bitop3_b32 v5, v2, s10, v4 bitop3:0xde
	v_bitop3_b32 v4, v2, s16, v4 bitop3:0xde
	s_addc_u32 s5, s5, 0
	v_lshlrev_b32_e32 v2, 2, v3
	v_mov_b32_e32 v3, v199
	v_lshl_add_u64 v[206:207], s[4:5], 0, v[2:3]
	v_lshlrev_b32_e32 v2, 14, v6
	v_and_b32_e32 v2, 0xffff8000, v2
	v_lshl_add_u32 v2, v7, 11, v2
	v_and_b32_e32 v3, 1, v6
	v_lshl_or_b32 v2, v3, 6, v2
	v_lshl_add_u32 v2, v10, 1, v2
	v_mov_b32_e32 v3, v199
	v_lshl_add_u64 v[2:3], s[72:73], 0, v[2:3]
	s_mov_b64 s[4:5], 0x9681080
	v_lshl_add_u64 v[208:209], v[2:3], 0, s[4:5]
	v_lshlrev_b32_e32 v2, 14, v9
	v_and_b32_e32 v2, 0xffff8000, v2
	v_lshl_add_u32 v2, v11, 11, v2
	v_and_b32_e32 v3, 1, v9
	v_lshl_or_b32 v2, v3, 6, v2
	s_waitcnt vmcnt(6)
	v_lshl_add_u32 v2, v12, 1, v2
	v_mov_b32_e32 v3, v199
	v_lshl_add_u64 v[2:3], s[72:73], 0, v[2:3]
	v_add_u32_e32 v220, 16, v4
	s_mov_b32 s1, 0
	v_mov_b32_e32 v203, v199
	v_mov_b32_e32 v205, v199
	v_lshl_add_u64 v[210:211], v[2:3], 0, s[4:5]
	v_add_u32_e32 v221, 0x10000, v220
	v_add_u32_e32 v222, 16, v5
	s_mov_b64 s[4:5], 0x100
	s_add_i32 s49, s27, 0xc000
	s_add_i32 s50, s27, 0xe000
	s_mov_b32 s51, 0
	v_readlane_b32 s60, v255, 51
	s_barrier
	v_readlane_b32 s61, v255, 1
	s_branch .LBB0_818
